# strategy 2 (epilogue de-serialisation): out-GEMM epilogue touches the residual rows of all row groups up front
# baseline (speedup 1.0000x reference)
.LBB0_810:
	v_lshl_add_u32 v164, s42, 8, v1
	v_lshl_or_b32 v162, s12, 8, v171
	v_ashrrev_i32_e32 v165, 31, v164
	v_ashrrev_i32_e32 v163, 31, v162
	v_lshlrev_b64 v[130:131], 13, v[164:165]
	v_lshl_add_u64 v[130:131], s[36:37], 0, v[130:131]
	v_lshlrev_b64 v[132:133], 2, v[162:163]
	v_lshl_add_u64 v[130:131], v[130:131], 0, v[132:133]
	global_load_dwordx4 v[178:181], v[130:131], off
	global_load_dwordx4 v[182:185], v[130:131], off offset:16
	global_load_dwordx4 v[186:189], v[130:131], off offset:512
	global_load_dwordx4 v[190:193], v[130:131], off offset:528
	v_lshl_add_u64 v[194:195], 2, 17, v[130:131]
	global_load_dword v196, v[194:195], off
	global_load_dword v197, v[194:195], off offset:512
	v_lshl_add_u64 v[194:195], 3, 17, v[130:131]
	global_load_dword v196, v[194:195], off
	global_load_dword v197, v[194:195], off offset:512
	v_lshl_add_u64 v[194:195], 8, 17, v[130:131]
	global_load_dword v196, v[194:195], off
	global_load_dword v197, v[194:195], off offset:512
	v_lshl_add_u64 v[194:195], 9, 17, v[130:131]
	global_load_dword v196, v[194:195], off
	global_load_dword v197, v[194:195], off offset:512
	v_lshl_add_u64 v[194:195], 10, 17, v[130:131]
	global_load_dword v196, v[194:195], off
	global_load_dword v197, v[194:195], off offset:512
	v_lshl_add_u64 v[194:195], 11, 17, v[130:131]
	global_load_dword v196, v[194:195], off
	global_load_dword v197, v[194:195], off offset:512
	s_nop 0
	s_nop 0
	s_nop 0
	s_nop 0
	s_nop 0
	s_nop 0
	s_nop 0
	s_nop 0
	s_nop 0
	s_nop 0
	s_nop 0
	s_nop 0
	v_or_b32_e32 v166, 16, v164
	v_ashrrev_i32_e32 v167, 31, v166
	v_lshlrev_b64 v[130:131], 13, v[166:167]
	v_lshl_add_u64 v[130:131], s[36:37], 0, v[130:131]
	v_lshl_add_u64 v[134:135], v[130:131], 0, v[132:133]
	global_load_dwordx4 v[138:141], v[134:135], off offset:16
	global_load_dwordx4 v[142:145], v[134:135], off
	global_load_dwordx4 v[130:133], v[134:135], off offset:528
	s_nop 0
	global_load_dwordx4 v[134:137], v[134:135], off offset:512
	v_and_b32_e32 v169, 64, v175
	v_xor_b32_e32 v168, 16, v175
	v_add_u32_e32 v169, 64, v169
	v_cmp_lt_i32_e32 vcc, v168, v169
	v_xor_b32_e32 v176, 32, v175
	s_lshl_b32 s42, s12, 2
	v_cndmask_b32_e32 v177, v175, v168, vcc
	v_lshlrev_b32_e32 v177, 2, v177
	v_cmp_lt_i32_e32 vcc, v176, v169
	v_lshlrev_b64 v[168:169], 12, v[164:165]
	s_ashr_i32 s43, s42, 31
	v_cndmask_b32_e32 v176, v175, v176, vcc
	v_lshlrev_b32_e32 v176, 2, v176
	s_waitcnt vmcnt(0)
	v_pk_add_f32 v[128:129], v[128:129], v[180:181]
	v_pk_add_f32 v[126:127], v[126:127], v[178:179]
	v_pk_add_f32 v[122:123], v[122:123], v[182:183]
	v_pk_add_f32 v[118:119], v[118:119], v[186:187]
	v_pk_add_f32 v[180:181], v[114:115], v[190:191]
	v_pk_add_f32 v[178:179], v[116:117], v[192:193]
	v_mul_f32_e32 v182, v127, v127
	v_mul_f32_e32 v183, v123, v123
	v_cvt_pk_bf16_f32 v114, v126, v127
	v_cvt_pk_bf16_f32 v116, v122, v123
	v_mul_f32_e32 v123, v119, v119
	v_mul_f32_e32 v127, v181, v181
	v_pk_add_f32 v[124:125], v[124:125], v[184:185]
	v_pk_add_f32 v[120:121], v[120:121], v[188:189]
	v_fmac_f32_e32 v182, v126, v126
	v_fmac_f32_e32 v183, v122, v122
	v_fmac_f32_e32 v123, v118, v118
	v_fmac_f32_e32 v127, v180, v180
	v_fmac_f32_e32 v182, v128, v128
	v_fmac_f32_e32 v183, v124, v124
	v_fmac_f32_e32 v123, v120, v120
	v_fmac_f32_e32 v127, v178, v178
	v_fmac_f32_e32 v182, v129, v129
	v_fmac_f32_e32 v183, v125, v125
	v_fmac_f32_e32 v123, v121, v121
	v_fmac_f32_e32 v127, v179, v179
	v_add_f32_e32 v122, v182, v183
	v_add_f32_e32 v123, v123, v127
	v_cvt_pk_bf16_f32 v117, v124, v125
	v_add_f32_e32 v124, v122, v123
	ds_bpermute_b32 v125, v177, v124
	v_lshl_add_u64 v[122:123], s[16:17], 0, v[168:169]
	v_cvt_pk_bf16_f32 v115, v128, v129
	v_lshl_add_u64 v[122:123], v[162:163], 1, v[122:123]
	global_store_dwordx4 v[122:123], v[114:117], off
	s_waitcnt lgkmcnt(0)
	s_nop 0
	v_add_f32_e32 v114, v124, v125
	ds_bpermute_b32 v115, v176, v114
	v_cvt_pk_bf16_f32 v116, v118, v119
	v_cvt_pk_bf16_f32 v117, v120, v121
	v_cvt_pk_bf16_f32 v118, v180, v181
	v_cvt_pk_bf16_f32 v119, v178, v179
	global_store_dwordx4 v[122:123], v[116:119], off offset:256
	s_and_saveexec_b64 s[44:45], s[6:7]
	s_cbranch_execz .LBB0_812
	v_lshlrev_b64 v[116:117], 7, v[164:165]
	v_lshl_add_u64 v[116:117], s[18:19], 0, v[116:117]
	v_lshl_add_u64 v[116:117], s[42:43], 2, v[116:117]
	s_lshl_b32 s12, s75, 2
	v_lshl_add_u64 v[116:117], v[116:117], 0, s[12:13]
	s_waitcnt lgkmcnt(0)
	v_add_f32_e32 v114, v114, v115
	global_store_dword v[116:117], v114, off
